# in-proj A: next unit's accumulators zeroed by 8 MFMAs (zero operands) on the idle matrix pipe during the epilogue instead of 64 v_mov_b64 at its end; on top of v78
# speedup vs baseline: 1.0001x; 1.0001x over previous
;     __device__ __forceinline__ void side_issue(Side& s, int ui, int c, int wid, int lane) const {
;         s.row = (c * upc + ui) * 8 + wid;
;         if (MODE == 0 && s.row < xrows) { const f32x4* xr = (const f32x4*)(xs + (size_t)s.row * 1024) + lane;
; #pragma unroll
;             for (int j = 0; j < 4; ++j) s.v[j] = __builtin_nontemporal_load(xr + 64 * j); }
;     ...
;         typename Epi::Side side_; E.side_issue(side_, ui, S.c, wid, lane);
.LBB0_221:
	v_mov_b32_e32 v238, 0
	v_mov_b32_e32 v239, 0
	v_mov_b32_e32 v240, 0
	v_mov_b32_e32 v241, 0
	s_add_i32 s2, s27, s43
	s_lshl_b32 s2, s2, 3
	s_add_i32 s76, s2, s14
	s_cmp_lt_i32 s76, s95
	s_cselect_b64 s[80:81], -1, 0
	s_cmp_ge_i32 s76, s95
	s_cbranch_scc1 .LBB0_223
	s_ashr_i32 s77, s76, 31
	s_lshl_b64 s[38:39], s[76:77], 12
	v_lshl_add_u64 v[198:199], v[174:175], 0, s[38:39]
	global_load_dwordx4 v[210:213], v[198:199], off nt
	global_load_dwordx4 v[206:209], v[198:199], off offset:1024 nt
	global_load_dwordx4 v[202:205], v[198:199], off offset:2048 nt
	s_nop 0
	global_load_dwordx4 v[198:201], v[198:199], off offset:3072 nt

; __device__ __forceinline__ float sum_x16(float v) { float a, b; swap16(v, a, b); return a + b; }
; __device__ __forceinline__ float sum_x32(float v) { float a, b; swap32(v, a, b); return a + b; }
; __device__ __forceinline__ void st16_wt(void* p, u32x4 v) { if (WT_STORES) asm volatile("global_store_dwordx4 %0, %1, off sc1\n\ts_nop 1" :: "v"(p), "v"(v) : "memory"); else *(u32x4*)p = v; }
; __device__ __forceinline__ unsigned cvt_pk_bf16(float lo, float hi) { unsigned r; asm volatile("v_cvt_pk_bf16_f32 %0, %1, %2" : "=v"(r) : "v"(lo), "v"(hi)); return r; }
;     __device__ __forceinline__ void operator()(const f32x4 (&acc)[2][2][4][2], const Unit& u, int wr, int wc, int fr, int fq, const bool reuse, PG8_LAS float* rscr, PG8_LAS const float* gains) const {
;     ...
; #pragma unroll
;         for (int ai = 0; ai < 2; ++ai)
; #pragma unroll
;             for (int m = 0; m < 4; ++m) {
;                 const int r = u.pm * BM + ai * HALF + wr * 64 + m * 16 + fr;
;                 const float rsv = (MODE == 0) ? 1.0f : rsvv[ai][m];
;                 f32x4 v[2][2];
; #pragma unroll
;                 for (int bj = 0; bj < 2; ++bj)
; #pragma unroll
;                     for (int n = 0; n < 2; ++n) v[bj][n] = acc[ai][bj][m][n] * rsv;
;                 if (type < 2) {
;                     float ss = 0.f;
; #pragma unroll
;                     for (int bj = 0; bj < 2; ++bj)
; #pragma unroll
;                         for (int n = 0; n < 2; ++n) { const f32x4 x = v[bj][n]; ss += (x[0] * x[0] + x[1] * x[1]) + (x[2] * x[2] + x[3] * x[3]); }
;                     ss = sum_x16(ss); ss = sum_x32(ss);
;                     const float inv = __builtin_amdgcn_rsqf(ss * (1.0f / 64.0f) + RMS_EPS);
; #pragma unroll
;                     for (int bj = 0; bj < 2; ++bj)
; #pragma unroll
;                         for (int n = 0; n < 2; ++n) v[bj][n] = v[bj][n] * gv[bj][n] * inv;
;                 }
;                 bf16_t* p = p0 + (size_t)(8 * ai + m) * step16;
; #pragma unroll
;                 for (int bj = 0; bj < 2; ++bj) { u32x4 w; w.x = cvt_pk_bf16(v[bj][0][0], v[bj][0][1]); w.y = cvt_pk_bf16(v[bj][0][2], v[bj][0][3]); w.z = cvt_pk_bf16(v[bj][1][0], v[bj][1][1]); w.w = cvt_pk_bf16(v[bj][1][2], v[bj][1][3]);
;                     st16_wt(p + 32 * bj, w); }
.LBB0_236:
	s_nop 0
	v_lshl_add_u64 v[112:113], v[128:129], 0, s[88:89]
	v_mfma_f32_32x32x16_bf16 v[128:143], v[238:241], v[238:241], 0
	s_and_b64 vcc, exec, s[38:39]
	v_cvt_pk_bf16_f32 v100, v100, v101
	v_cvt_pk_bf16_f32 v101, v102, v103
	v_cvt_pk_bf16_f32 v102, v96, v97
	v_cvt_pk_bf16_f32 v103, v98, v99
	global_store_dwordx4 v[112:113], v[100:103], off
	v_cvt_pk_bf16_f32 v96, v108, v109
	v_cvt_pk_bf16_f32 v97, v110, v111
	v_cvt_pk_bf16_f32 v98, v104, v105
	v_cvt_pk_bf16_f32 v99, v106, v107
	global_store_dwordx4 v[112:113], v[96:99], off offset:64
	s_cbranch_vccnz .LBB0_238
	s_nop 0
	v_pk_mul_f32 v[96:97], v[80:81], v[80:81]
	v_pk_fma_f32 v[96:97], v[82:83], v[82:83], v[96:97]
	v_pk_fma_f32 v[96:97], v[84:85], v[84:85], v[96:97]
	v_pk_fma_f32 v[96:97], v[86:87], v[86:87], v[96:97]
	v_pk_fma_f32 v[96:97], v[88:89], v[88:89], v[96:97]
	v_pk_fma_f32 v[96:97], v[90:91], v[90:91], v[96:97]
	v_pk_fma_f32 v[96:97], v[92:93], v[92:93], v[96:97]
	v_pk_fma_f32 v[96:97], v[94:95], v[94:95], v[96:97]
	v_add_f32_e32 v96, v96, v97
	v_mov_b32_e32 v97, v96
	s_nop 1
	v_permlane16_swap_b32_e32 v96, v97
	v_add_f32_e32 v96, v96, v97
	v_mov_b32_e32 v97, v96
	s_nop 1
	v_permlane32_swap_b32_e32 v96, v97
	v_add_f32_e32 v96, v96, v97
	v_fmamk_f32 v96, v96, 0x3c800000, v190
	v_rsq_f32_e32 v96, v96
	s_waitcnt lgkmcnt(0)
	v_pk_mul_f32 v[86:87], v[86:87], v[158:159]
	v_pk_mul_f32 v[84:85], v[84:85], v[156:157]
	v_pk_mul_f32 v[82:83], v[82:83], v[154:155]
	v_pk_mul_f32 v[80:81], v[80:81], v[152:153]
	v_pk_mul_f32 v[94:95], v[94:95], v[150:151]
	v_pk_mul_f32 v[92:93], v[92:93], v[148:149]
	v_pk_mul_f32 v[90:91], v[90:91], v[146:147]
	v_pk_mul_f32 v[88:89], v[88:89], v[144:145]
	v_pk_mul_f32 v[86:87], v[86:87], v[96:97] op_sel_hi:[1,0]
	v_pk_mul_f32 v[84:85], v[84:85], v[96:97] op_sel_hi:[1,0]
	v_pk_mul_f32 v[82:83], v[82:83], v[96:97] op_sel_hi:[1,0]
	v_pk_mul_f32 v[80:81], v[80:81], v[96:97] op_sel_hi:[1,0]
	v_pk_mul_f32 v[94:95], v[94:95], v[96:97] op_sel_hi:[1,0]
	v_pk_mul_f32 v[92:93], v[92:93], v[96:97] op_sel_hi:[1,0]
	v_pk_mul_f32 v[90:91], v[90:91], v[96:97] op_sel_hi:[1,0]
	v_pk_mul_f32 v[88:89], v[88:89], v[96:97] op_sel_hi:[1,0]
.LBB0_238:
	s_nop 0
	v_lshl_add_u64 v[96:97], v[112:113], 0, s[88:89]
	v_mfma_f32_32x32x16_bf16 v[112:127], v[238:241], v[238:241], 0
	s_and_b64 vcc, exec, s[38:39]
	v_cvt_pk_bf16_f32 v84, v84, v85
	v_cvt_pk_bf16_f32 v85, v86, v87
	v_cvt_pk_bf16_f32 v86, v80, v81
	v_cvt_pk_bf16_f32 v87, v82, v83
	global_store_dwordx4 v[96:97], v[84:87], off
	v_cvt_pk_bf16_f32 v80, v92, v93
	v_cvt_pk_bf16_f32 v81, v94, v95
	v_cvt_pk_bf16_f32 v82, v88, v89
	v_cvt_pk_bf16_f32 v83, v90, v91
	global_store_dwordx4 v[96:97], v[80:83], off offset:64
	s_cbranch_vccnz .LBB0_240
	s_nop 0
	v_pk_mul_f32 v[80:81], v[64:65], v[64:65]
	v_pk_fma_f32 v[80:81], v[66:67], v[66:67], v[80:81]
	v_pk_fma_f32 v[80:81], v[68:69], v[68:69], v[80:81]
	v_pk_fma_f32 v[80:81], v[70:71], v[70:71], v[80:81]
	v_pk_fma_f32 v[80:81], v[72:73], v[72:73], v[80:81]
	v_pk_fma_f32 v[80:81], v[74:75], v[74:75], v[80:81]
	v_pk_fma_f32 v[80:81], v[76:77], v[76:77], v[80:81]
	v_pk_fma_f32 v[80:81], v[78:79], v[78:79], v[80:81]
	v_add_f32_e32 v80, v80, v81
	v_mov_b32_e32 v81, v80
	s_nop 1
	v_permlane16_swap_b32_e32 v80, v81
	v_add_f32_e32 v80, v80, v81
	v_mov_b32_e32 v81, v80
	s_nop 1
	v_permlane32_swap_b32_e32 v80, v81
	v_add_f32_e32 v80, v80, v81
	v_fmamk_f32 v80, v80, 0x3c800000, v190
	v_rsq_f32_e32 v80, v80
	s_waitcnt lgkmcnt(0)
	v_pk_mul_f32 v[70:71], v[70:71], v[158:159]
	v_pk_mul_f32 v[68:69], v[68:69], v[156:157]
	v_pk_mul_f32 v[66:67], v[66:67], v[154:155]
	v_pk_mul_f32 v[64:65], v[64:65], v[152:153]
	v_pk_mul_f32 v[78:79], v[78:79], v[150:151]
	v_pk_mul_f32 v[76:77], v[76:77], v[148:149]
	v_pk_mul_f32 v[74:75], v[74:75], v[146:147]
	v_pk_mul_f32 v[72:73], v[72:73], v[144:145]
	v_pk_mul_f32 v[70:71], v[70:71], v[80:81] op_sel_hi:[1,0]
	v_pk_mul_f32 v[68:69], v[68:69], v[80:81] op_sel_hi:[1,0]
	v_pk_mul_f32 v[66:67], v[66:67], v[80:81] op_sel_hi:[1,0]
	v_pk_mul_f32 v[64:65], v[64:65], v[80:81] op_sel_hi:[1,0]
	v_pk_mul_f32 v[78:79], v[78:79], v[80:81] op_sel_hi:[1,0]
	v_pk_mul_f32 v[76:77], v[76:77], v[80:81] op_sel_hi:[1,0]
	v_pk_mul_f32 v[74:75], v[74:75], v[80:81] op_sel_hi:[1,0]
	v_pk_mul_f32 v[72:73], v[72:73], v[80:81] op_sel_hi:[1,0]
.LBB0_240:
	s_nop 0
	v_mad_u64_u32 v[80:81], s[12:13], s72, 10, v[96:97]
	v_mov_b32_e32 v254, v80
	v_mov_b32_e32 v255, v81
	v_mfma_f32_32x32x16_bf16 v[96:111], v[238:241], v[238:241], 0
	s_and_b64 vcc, exec, s[38:39]
	v_cvt_pk_bf16_f32 v244, v68, v69
	v_cvt_pk_bf16_f32 v245, v70, v71
	v_cvt_pk_bf16_f32 v246, v64, v65
	v_cvt_pk_bf16_f32 v247, v66, v67
	v_cvt_pk_bf16_f32 v248, v76, v77
	v_cvt_pk_bf16_f32 v249, v78, v79
	v_cvt_pk_bf16_f32 v250, v72, v73
	v_cvt_pk_bf16_f32 v251, v74, v75
	s_cbranch_vccnz .LBB0_242
	s_nop 0
	v_pk_mul_f32 v[64:65], v[48:49], v[48:49]
	v_pk_fma_f32 v[64:65], v[50:51], v[50:51], v[64:65]
	v_pk_fma_f32 v[64:65], v[52:53], v[52:53], v[64:65]
	v_pk_fma_f32 v[64:65], v[54:55], v[54:55], v[64:65]
	v_pk_fma_f32 v[64:65], v[56:57], v[56:57], v[64:65]
	v_pk_fma_f32 v[64:65], v[58:59], v[58:59], v[64:65]
	v_pk_fma_f32 v[64:65], v[60:61], v[60:61], v[64:65]
	v_pk_fma_f32 v[64:65], v[62:63], v[62:63], v[64:65]
	v_add_f32_e32 v64, v64, v65
	v_mov_b32_e32 v65, v64
	s_nop 1
	v_permlane16_swap_b32_e32 v64, v65
	v_add_f32_e32 v64, v64, v65
	v_mov_b32_e32 v65, v64
	s_nop 1
	v_permlane32_swap_b32_e32 v64, v65
	v_add_f32_e32 v64, v64, v65
	v_fmamk_f32 v64, v64, 0x3c800000, v190
	v_rsq_f32_e32 v64, v64
	s_waitcnt lgkmcnt(0)
	v_pk_mul_f32 v[54:55], v[54:55], v[158:159]
	v_pk_mul_f32 v[52:53], v[52:53], v[156:157]
	v_pk_mul_f32 v[50:51], v[50:51], v[154:155]
	v_pk_mul_f32 v[48:49], v[48:49], v[152:153]
	v_pk_mul_f32 v[62:63], v[62:63], v[150:151]
	v_pk_mul_f32 v[60:61], v[60:61], v[148:149]
	v_pk_mul_f32 v[58:59], v[58:59], v[146:147]
	v_pk_mul_f32 v[56:57], v[56:57], v[144:145]
	v_pk_mul_f32 v[54:55], v[54:55], v[64:65] op_sel_hi:[1,0]
	v_pk_mul_f32 v[52:53], v[52:53], v[64:65] op_sel_hi:[1,0]
	v_pk_mul_f32 v[50:51], v[50:51], v[64:65] op_sel_hi:[1,0]
	v_pk_mul_f32 v[48:49], v[48:49], v[64:65] op_sel_hi:[1,0]
	v_pk_mul_f32 v[62:63], v[62:63], v[64:65] op_sel_hi:[1,0]
	v_pk_mul_f32 v[60:61], v[60:61], v[64:65] op_sel_hi:[1,0]
	v_pk_mul_f32 v[58:59], v[58:59], v[64:65] op_sel_hi:[1,0]
	v_pk_mul_f32 v[56:57], v[56:57], v[64:65] op_sel_hi:[1,0]
; __device__ __forceinline__ float sum_x16(float v) { float a, b; swap16(v, a, b); return a + b; }
; __device__ __forceinline__ float sum_x32(float v) { float a, b; swap32(v, a, b); return a + b; }
; __device__ __forceinline__ void st16_wt(void* p, u32x4 v) { if (WT_STORES) asm volatile("global_store_dwordx4 %0, %1, off sc1\n\ts_nop 1" :: "v"(p), "v"(v) : "memory"); else *(u32x4*)p = v; }
; __device__ __forceinline__ unsigned cvt_pk_bf16(float lo, float hi) { unsigned r; asm volatile("v_cvt_pk_bf16_f32 %0, %1, %2" : "=v"(r) : "v"(lo), "v"(hi)); return r; }
;     __device__ __forceinline__ void operator()(const f32x4 (&acc)[2][2][4][2], const Unit& u, int wr, int wc, int fr, int fq, const bool reuse, PG8_LAS float* rscr, PG8_LAS const float* gains) const {
;     ...
; #pragma unroll
;         for (int ai = 0; ai < 2; ++ai)
; #pragma unroll
;             for (int m = 0; m < 4; ++m) {
;                 const int r = u.pm * BM + ai * HALF + wr * 64 + m * 16 + fr;
;                 const float rsv = (MODE == 0) ? 1.0f : rsvv[ai][m];
;                 f32x4 v[2][2];
; #pragma unroll
;                 for (int bj = 0; bj < 2; ++bj)
; #pragma unroll
;                     for (int n = 0; n < 2; ++n) v[bj][n] = acc[ai][bj][m][n] * rsv;
;                 if (type < 2) {
;                     float ss = 0.f;
; #pragma unroll
;                     for (int bj = 0; bj < 2; ++bj)
; #pragma unroll
;                         for (int n = 0; n < 2; ++n) { const f32x4 x = v[bj][n]; ss += (x[0] * x[0] + x[1] * x[1]) + (x[2] * x[2] + x[3] * x[3]); }
;                     ss = sum_x16(ss); ss = sum_x32(ss);
;                     const float inv = __builtin_amdgcn_rsqf(ss * (1.0f / 64.0f) + RMS_EPS);
; #pragma unroll
;                     for (int bj = 0; bj < 2; ++bj)
; #pragma unroll
;                         for (int n = 0; n < 2; ++n) v[bj][n] = v[bj][n] * gv[bj][n] * inv;
;                 }
;                 bf16_t* p = p0 + (size_t)(8 * ai + m) * step16;
; #pragma unroll
;                 for (int bj = 0; bj < 2; ++bj) { u32x4 w; w.x = cvt_pk_bf16(v[bj][0][0], v[bj][0][1]); w.y = cvt_pk_bf16(v[bj][0][2], v[bj][0][3]); w.z = cvt_pk_bf16(v[bj][1][0], v[bj][1][1]); w.w = cvt_pk_bf16(v[bj][1][2], v[bj][1][3]);
;                     st16_wt(p + 32 * bj, w); }
.LBB0_242:
	s_nop 0
	v_lshl_add_u64 v[64:65], v[80:81], 0, s[88:89]
	v_mfma_f32_32x32x16_bf16 v[80:95], v[238:241], v[238:241], 0
	s_and_b64 vcc, exec, s[38:39]
	v_cvt_pk_bf16_f32 v214, v52, v53
	v_cvt_pk_bf16_f32 v215, v54, v55
	v_cvt_pk_bf16_f32 v216, v48, v49
	v_cvt_pk_bf16_f32 v217, v50, v51
	v_cvt_pk_bf16_f32 v218, v60, v61
	v_cvt_pk_bf16_f32 v219, v62, v63
	v_cvt_pk_bf16_f32 v220, v56, v57
	v_cvt_pk_bf16_f32 v221, v58, v59
	s_cbranch_vccnz .LBB0_244
	s_nop 0
	v_pk_mul_f32 v[48:49], v[32:33], v[32:33]
	v_pk_fma_f32 v[48:49], v[34:35], v[34:35], v[48:49]
	v_pk_fma_f32 v[48:49], v[36:37], v[36:37], v[48:49]
	v_pk_fma_f32 v[48:49], v[38:39], v[38:39], v[48:49]
	v_pk_fma_f32 v[48:49], v[40:41], v[40:41], v[48:49]
	v_pk_fma_f32 v[48:49], v[42:43], v[42:43], v[48:49]
	v_pk_fma_f32 v[48:49], v[44:45], v[44:45], v[48:49]
	v_pk_fma_f32 v[48:49], v[46:47], v[46:47], v[48:49]
	v_add_f32_e32 v48, v48, v49
	v_mov_b32_e32 v49, v48
	s_nop 1
	v_permlane16_swap_b32_e32 v48, v49
	v_add_f32_e32 v48, v48, v49
	v_mov_b32_e32 v49, v48
	s_nop 1
	v_permlane32_swap_b32_e32 v48, v49
	v_add_f32_e32 v48, v48, v49
	v_fmamk_f32 v48, v48, 0x3c800000, v190
	v_rsq_f32_e32 v48, v48
	s_waitcnt lgkmcnt(0)
	v_pk_mul_f32 v[38:39], v[38:39], v[158:159]
	v_pk_mul_f32 v[36:37], v[36:37], v[156:157]
	v_pk_mul_f32 v[34:35], v[34:35], v[154:155]
	v_pk_mul_f32 v[32:33], v[32:33], v[152:153]
	v_pk_mul_f32 v[46:47], v[46:47], v[150:151]
	v_pk_mul_f32 v[44:45], v[44:45], v[148:149]
	v_pk_mul_f32 v[42:43], v[42:43], v[146:147]
	v_pk_mul_f32 v[40:41], v[40:41], v[144:145]
	v_pk_mul_f32 v[38:39], v[38:39], v[48:49] op_sel_hi:[1,0]
	v_pk_mul_f32 v[36:37], v[36:37], v[48:49] op_sel_hi:[1,0]
	v_pk_mul_f32 v[34:35], v[34:35], v[48:49] op_sel_hi:[1,0]
	v_pk_mul_f32 v[32:33], v[32:33], v[48:49] op_sel_hi:[1,0]
	v_pk_mul_f32 v[46:47], v[46:47], v[48:49] op_sel_hi:[1,0]
	v_pk_mul_f32 v[44:45], v[44:45], v[48:49] op_sel_hi:[1,0]
	v_pk_mul_f32 v[42:43], v[42:43], v[48:49] op_sel_hi:[1,0]
	v_pk_mul_f32 v[40:41], v[40:41], v[48:49] op_sel_hi:[1,0]
.LBB0_244:
	s_nop 0
	v_lshl_add_u64 v[48:49], v[64:65], 0, s[88:89]
	v_mfma_f32_32x32x16_bf16 v[64:79], v[238:241], v[238:241], 0
	s_and_b64 vcc, exec, s[38:39]
	v_cvt_pk_bf16_f32 v0, v36, v37
	v_cvt_pk_bf16_f32 v1, v38, v39
	v_cvt_pk_bf16_f32 v2, v32, v33
	v_cvt_pk_bf16_f32 v3, v34, v35
	v_cvt_pk_bf16_f32 v4, v44, v45
	v_cvt_pk_bf16_f32 v5, v46, v47
	v_cvt_pk_bf16_f32 v6, v40, v41
	v_cvt_pk_bf16_f32 v7, v42, v43
	s_cbranch_vccnz .LBB0_246
	s_nop 0
	v_pk_mul_f32 v[32:33], v[16:17], v[16:17]
	v_pk_fma_f32 v[32:33], v[18:19], v[18:19], v[32:33]
	v_pk_fma_f32 v[32:33], v[20:21], v[20:21], v[32:33]
	v_pk_fma_f32 v[32:33], v[22:23], v[22:23], v[32:33]
	v_pk_fma_f32 v[32:33], v[24:25], v[24:25], v[32:33]
	v_pk_fma_f32 v[32:33], v[26:27], v[26:27], v[32:33]
	v_pk_fma_f32 v[32:33], v[28:29], v[28:29], v[32:33]
	v_pk_fma_f32 v[32:33], v[30:31], v[30:31], v[32:33]
	v_add_f32_e32 v32, v32, v33
	v_mov_b32_e32 v33, v32
	s_nop 1
	v_permlane16_swap_b32_e32 v32, v33
	v_add_f32_e32 v32, v32, v33
	v_mov_b32_e32 v33, v32
	s_nop 1
	v_permlane32_swap_b32_e32 v32, v33
	v_add_f32_e32 v32, v32, v33
	v_fmamk_f32 v32, v32, 0x3c800000, v190
	v_rsq_f32_e32 v32, v32
	s_waitcnt lgkmcnt(0)
	v_pk_mul_f32 v[22:23], v[22:23], v[158:159]
	v_pk_mul_f32 v[20:21], v[20:21], v[156:157]
	v_pk_mul_f32 v[18:19], v[18:19], v[154:155]
	v_pk_mul_f32 v[16:17], v[16:17], v[152:153]
	v_pk_mul_f32 v[26:27], v[26:27], v[150:151]
	v_pk_mul_f32 v[24:25], v[24:25], v[148:149]
	v_pk_mul_f32 v[30:31], v[30:31], v[146:147]
	v_pk_mul_f32 v[28:29], v[28:29], v[144:145]
	v_pk_mul_f32 v[22:23], v[22:23], v[32:33] op_sel_hi:[1,0]
	v_pk_mul_f32 v[20:21], v[20:21], v[32:33] op_sel_hi:[1,0]
	v_pk_mul_f32 v[18:19], v[18:19], v[32:33] op_sel_hi:[1,0]
	v_pk_mul_f32 v[16:17], v[16:17], v[32:33] op_sel_hi:[1,0]
	v_pk_mul_f32 v[26:27], v[26:27], v[32:33] op_sel_hi:[1,0]
	v_pk_mul_f32 v[24:25], v[24:25], v[32:33] op_sel_hi:[1,0]
	v_pk_mul_f32 v[30:31], v[30:31], v[32:33] op_sel_hi:[1,0]
	v_pk_mul_f32 v[28:29], v[28:29], v[32:33] op_sel_hi:[1,0]
; __device__ __forceinline__ float wave_sum(float v) { v += dpp_mov<0xB1>(v); v += dpp_mov<0x4E>(v); v += dpp_mov<0x141>(v); v += dpp_mov<0x140>(v); v = sum_x16(v); return sum_x32(v); }
; __device__ __forceinline__ unsigned cvt_pk_bf16(float lo, float hi) { unsigned r; asm volatile("v_cvt_pk_bf16_f32 %0, %1, %2" : "=v"(r) : "v"(lo), "v"(hi)); return r; }
; #define PG8_ZERO4(x) do { unsigned long long z0_, z1_; asm volatile("v_mov_b64 %0, 0\n\tv_mov_b64 %1, 0" : "=v"(z0_), "=v"(z1_)); typedef unsigned long long u64x2_ __attribute__((ext_vector_type(2))); (x) = __builtin_bit_cast(f32x4, (u64x2_){z0_, z1_}); } while (0)
;     __device__ __forceinline__ void side_finish(const Side& s, int lane) const {
;         if (MODE == 0 && s.row < xrows) {
;             float q = 0.f;
; #pragma unroll
;             for (int j = 0; j < 4; ++j) q += (s.v[j][0] * s.v[j][0] + s.v[j][1] * s.v[j][1]) + (s.v[j][2] * s.v[j][2] + s.v[j][3] * s.v[j][3]);
;             const float rstd = __builtin_amdgcn_rsqf(wave_sum(q) * (1.0f / 1024.0f) + 1e-6f);
;             const bool odd = lane & 1;
;             bf16_t* orow = xd + (size_t)s.row * 1024 + 4 * (lane & ~1);
; #pragma unroll
;             for (int jp = 0; jp < 2; ++jp) {
;                 const int ja = 2 * jp, jb = 2 * jp + 1;
;                 const unsigned pax = cvt_pk_bf16(s.v[ja][0] * rstd, s.v[ja][1] * rstd), pay = cvt_pk_bf16(s.v[ja][2] * rstd, s.v[ja][3] * rstd);
;                 const unsigned pbx = cvt_pk_bf16(s.v[jb][0] * rstd, s.v[jb][1] * rstd), pby = cvt_pk_bf16(s.v[jb][2] * rstd, s.v[jb][3] * rstd);
;                 const unsigned rx = (unsigned)__builtin_amdgcn_update_dpp(0, (int)(odd ? pax : pbx), 0xB1, 0xF, 0xF, true), ry = (unsigned)__builtin_amdgcn_update_dpp(0, (int)(odd ? pay : pby), 0xB1, 0xF, 0xF, true);
;                 u32x4 w; w.x = odd ? rx : pax; w.y = odd ? ry : pay; w.z = odd ? pbx : rx; w.w = odd ? pby : ry;
;                 *(u32x4*)(orow + (odd ? 256 * jb : 256 * ja)) = w;
;             }
;     ...
; #pragma unroll
;         for (int a = 0; a < 2; ++a)
; #pragma unroll
;             for (int b = 0; b < 2; ++b)
; #pragma unroll
;                 for (int m = 0; m < 4; ++m)
; #pragma unroll
;                     for (int n = 0; n < 2; ++n) PG8_ZERO4(acc[a][b][m][n]);
.LBB0_246:
	s_nop 0
	v_lshl_add_u64 v[32:33], v[48:49], 0, s[88:89]
	v_mfma_f32_32x32x16_bf16 v[48:63], v[238:241], v[238:241], 0
	v_mfma_f32_32x32x16_bf16 v[32:47], v[238:241], v[238:241], 0
	s_andn2_b64 vcc, exec, s[80:81]
	v_cvt_pk_bf16_f32 v8, v20, v21
	v_cvt_pk_bf16_f32 v9, v22, v23
	v_cvt_pk_bf16_f32 v10, v16, v17
	v_cvt_pk_bf16_f32 v11, v18, v19
	v_cvt_pk_bf16_f32 v12, v24, v25
	v_cvt_pk_bf16_f32 v13, v26, v27
	v_cvt_pk_bf16_f32 v14, v28, v29
	v_cvt_pk_bf16_f32 v15, v30, v31
	s_mov_b32 s101, 8
	s_cbranch_vccnz .LBB0_248
	s_waitcnt vmcnt(8)
	v_mul_f32_e32 v16, v211, v211
	v_mul_f32_e32 v17, v213, v213
	v_fmac_f32_e32 v16, v210, v210
	v_fmac_f32_e32 v17, v212, v212
	v_add_f32_e32 v16, v16, v17
	v_mul_f32_e32 v17, v207, v207
	v_mul_f32_e32 v18, v209, v209
	v_fmac_f32_e32 v17, v206, v206
	v_fmac_f32_e32 v18, v208, v208
	v_add_f32_e32 v17, v17, v18
	v_add_f32_e32 v16, v17, v16
	v_mul_f32_e32 v17, v203, v203
	v_mul_f32_e32 v18, v205, v205
	v_fmac_f32_e32 v17, v202, v202
	v_fmac_f32_e32 v18, v204, v204
	v_add_f32_e32 v17, v17, v18
	v_add_f32_e32 v16, v17, v16
	v_mul_f32_e32 v17, v199, v199
	v_mul_f32_e32 v18, v201, v201
	v_fmac_f32_e32 v17, v198, v198
	v_fmac_f32_e32 v18, v200, v200
	v_add_f32_e32 v17, v17, v18
	v_add_f32_e32 v16, v17, v16
	s_ashr_i32 s77, s76, 31
	s_lshl_b64 s[12:13], s[76:77], 11
	v_add_f32_dpp v16, v16, v16 quad_perm:[1,0,3,2] row_mask:0xf bank_mask:0xf bound_ctrl:1
	v_lshl_add_u64 v[20:21], v[176:177], 0, s[12:13]
	v_mov_b32_e32 v183, v161
	v_add_f32_dpp v16, v16, v16 quad_perm:[2,3,0,1] row_mask:0xf bank_mask:0xf bound_ctrl:1
	v_mov_b32_e32 v185, v161
	s_nop 0
	v_add_f32_dpp v16, v16, v16 row_half_mirror row_mask:0xf bank_mask:0xf bound_ctrl:1
	s_nop 1
	v_add_f32_dpp v16, v16, v16 row_mirror row_mask:0xf bank_mask:0xf bound_ctrl:1
	v_mov_b32_e32 v17, v16
	s_nop 1
	v_permlane16_swap_b32_e32 v16, v17
	v_add_f32_e32 v16, v16, v17
	v_mov_b32_e32 v17, v16
	s_nop 1
	v_permlane32_swap_b32_e32 v16, v17
	v_add_f32_e32 v16, v16, v17
	v_fmamk_f32 v16, v16, 0x3a800000, v190
	v_rsq_f32_e32 v24, v16
	s_nop 0
	v_mul_f32_e32 v16, v210, v24
	v_mul_f32_e32 v17, v211, v24
	v_cvt_pk_bf16_f32 v16, v16, v17
	v_mul_f32_e32 v17, v212, v24
	v_mul_f32_e32 v18, v213, v24
	v_cvt_pk_bf16_f32 v17, v17, v18
	v_mul_f32_e32 v18, v206, v24
	v_mul_f32_e32 v19, v207, v24
	v_cvt_pk_bf16_f32 v18, v18, v19
	v_mul_f32_e32 v19, v208, v24
	v_mul_f32_e32 v22, v209, v24
	v_cvt_pk_bf16_f32 v19, v19, v22
	v_cndmask_b32_e64 v22, v16, v18, s[34:35]
	v_cndmask_b32_e64 v23, v17, v19, s[34:35]
	s_nop 0
	v_mov_b32_dpp v22, v22 quad_perm:[1,0,3,2] row_mask:0xf bank_mask:0xf bound_ctrl:1
	v_mov_b32_dpp v23, v23 quad_perm:[1,0,3,2] row_mask:0xf bank_mask:0xf bound_ctrl:1
	v_cndmask_b32_e64 v16, v22, v16, s[34:35]
	v_cndmask_b32_e64 v17, v23, v17, s[34:35]
	v_cndmask_b32_e64 v18, v18, v22, s[34:35]
	v_cndmask_b32_e64 v19, v19, v23, s[34:35]
	v_lshl_add_u64 v[22:23], v[20:21], 0, v[182:183]
	global_store_dwordx4 v[22:23], v[16:19], off
	v_mul_f32_e32 v22, v201, v24
	v_lshl_add_u64 v[20:21], v[20:21], 0, v[184:185]
	v_mul_f32_e32 v16, v202, v24
	v_mul_f32_e32 v17, v203, v24
	v_cvt_pk_bf16_f32 v16, v16, v17
	v_mul_f32_e32 v17, v204, v24
	v_mul_f32_e32 v18, v205, v24
	v_cvt_pk_bf16_f32 v17, v17, v18
	v_mul_f32_e32 v18, v198, v24
	v_mul_f32_e32 v19, v199, v24
	v_cvt_pk_bf16_f32 v18, v18, v19
	v_mul_f32_e32 v19, v200, v24
	v_cvt_pk_bf16_f32 v19, v19, v22
	v_cndmask_b32_e64 v22, v16, v18, s[34:35]
	v_cndmask_b32_e64 v23, v17, v19, s[34:35]
	s_nop 0
	v_mov_b32_dpp v22, v22 quad_perm:[1,0,3,2] row_mask:0xf bank_mask:0xf bound_ctrl:1
	v_mov_b32_dpp v23, v23 quad_perm:[1,0,3,2] row_mask:0xf bank_mask:0xf bound_ctrl:1
	v_cndmask_b32_e64 v16, v22, v16, s[34:35]
	v_cndmask_b32_e64 v17, v23, v17, s[34:35]
	v_cndmask_b32_e64 v18, v18, v22, s[34:35]
	v_cndmask_b32_e64 v19, v19, v23, s[34:35]
	global_store_dwordx4 v[20:21], v[16:19], off
.LBB0_248:
	v_mfma_f32_32x32x16_bf16 v[16:31], v[238:241], v[238:241], 0
	s_andn2_b64 vcc, exec, s[36:37]
	s_mov_b64 s[36:37], -1
	s_cbranch_vccnz .LBB0_202
	s_andn2_b64 vcc, exec, s[20:21]
	s_cbranch_vccnz .LBB0_201
	s_barrier
	s_branch .LBB0_201
